# cross-half max exchange via v_permlane32_swap instead of ds_bpermute in diff main/tail loops and dil loop (stacked on v8)
# baseline (speedup 1.0000x reference)
; #define MFMA32(a, b, c) __builtin_amdgcn_mfma_f32_32x32x16_bf16((a), (b), (c), 0, 0, 0)
; DI f32x16 zero16() { f32x16 z; for (int i = 0; i < 16; ++i) z[i] = 0.f; return z; }
; DI void dil_attn_phase(int wv, const bf16_t* qk, const bf16_t* vt, float* oacc, float* stats, bf16_t* ob, int g, int dil) {
;     ...
;         for (int jt = (l0 >= 128) ? 0 : 4 - (l0 >> 5); jt < 5; ++jt) {
;             const int kl0 = l0 - 128 + 32 * jt;
;             const size_t krow = (size_t)b * SEQ + (size_t)(kl0 + prr) * dil + rph;
;             bf16x8 kf[8];
; #pragma unroll
;             for (int ks = 0; ks < 8; ++ks) kf[ks] = *(const bf16x8*)(qk + krow * 2048 + 1024 + head * 128 + ks * 16 + hh * 8);
;             const bf16_t* vb = vt + (size_t)(head * 128 + rr) * M_TOK + (size_t)b * SEQ + (size_t)rph * L + kl0 + 8 * hh;
;             bf16x8 vf[4][2];
; #pragma unroll
;             for (int d = 0; d < 4; ++d)
; #pragma unroll
;                 for (int s = 0; s < 2; ++s) vf[d][s] = *(const bf16x8*)(vb + (size_t)d * 32 * M_TOK + 16 * s);
;             f32x16 S = zero16();
; #pragma unroll
;             for (int ks = 0; ks < 8; ++ks) S = MFMA32(kf[ks], qf[ks], S);
;             float sv[16]; float mx = -INFINITY;
; #pragma unroll
;             for (int i = 0; i < 16; ++i) { const int dist = (l0 + rr) - (kl0 + (i & 7) + 16 * (i >> 3) + 8 * hh); float v = S[i] * c1 - slope2d * (float)dist; v = ((unsigned)dist <= 128u) ? v : -INFINITY; sv[i] = v; mx = fmaxf(mx, v); }
;             mx = fmaxf(mx, __shfl_xor(mx, 32));
.LBB0_281:
	v_ashrrev_i32_e32 v165, 31, v164
	v_mov_b32_e32 v182, v67
	s_ashr_i32 s13, s12, 31
	v_lshlrev_b64 v[66:67], s16, v[164:165]
	s_add_u32 s26, s25, s12
	v_lshl_add_u64 v[66:67], v[66:67], 0, s[4:5]
	s_addc_u32 s27, s10, s13
	v_lshlrev_b64 v[66:67], 12, v[66:67]
	v_lshl_add_u64 v[122:123], s[26:27], 1, v[160:161]
	v_lshl_add_u64 v[124:125], v[162:163], 0, v[66:67]
	global_load_dwordx4 v[130:133], v[122:123], off offset:-256
	global_load_dwordx4 v[126:129], v[122:123], off offset:-224
	global_load_dwordx4 v[66:69], v[124:125], off offset:2048
	global_load_dwordx4 v[114:117], v[124:125], off offset:2080
	global_load_dwordx4 v[118:121], v[124:125], off offset:2112
	global_load_dwordx4 v[200:203], v[124:125], off offset:2144
	global_load_dwordx4 v[204:207], v[124:125], off offset:2176
	global_load_dwordx4 v[208:211], v[124:125], off offset:2208
	global_load_dwordx4 v[212:215], v[124:125], off offset:2240
	global_load_dwordx4 v[184:187], v[124:125], off offset:2272
	s_mov_b32 s2, 0x1ff000
	v_add_co_u32_e32 v134, vcc, s2, v122
	v_add_u32_e32 v170, 23, v181
	s_nop 0
	v_addc_co_u32_e32 v135, vcc, 0, v123, vcc
	s_mov_b32 s2, 0x3ff000
	v_cvt_f32_i32_e32 v167, v170
	v_add_co_u32_e32 v136, vcc, s2, v122
	s_mov_b32 s2, 0x5ff000
	s_nop 0
	v_addc_co_u32_e32 v137, vcc, 0, v123, vcc
	v_add_co_u32_e32 v168, vcc, s2, v122
	v_add_u32_e32 v171, 22, v181
	s_nop 0
	v_addc_co_u32_e32 v169, vcc, 0, v123, vcc
	global_load_dwordx4 v[142:145], v[134:135], off offset:3840
	global_load_dwordx4 v[216:219], v[134:135], off offset:3872
	global_load_dwordx4 v[138:141], v[136:137], off offset:3840
	global_load_dwordx4 v[220:223], v[136:137], off offset:3872
	global_load_dwordx4 v[224:227], v[168:169], off offset:3840
	v_add_u32_e32 v183, 21, v181
	v_cmp_gt_u32_e32 vcc, s69, v170
	v_add_u32_e32 v188, 20, v181
	v_add_u32_e32 v189, 19, v181
	v_add_u32_e32 v190, 18, v181
	v_add_u32_e32 v191, 17, v181
	v_add_u32_e32 v192, 16, v181
	v_add_u32_e32 v193, 7, v181
	v_add_u32_e32 v194, 6, v181
	v_add_u32_e32 v195, 5, v181
	v_add_u32_e32 v196, 4, v181
	v_add_u32_e32 v197, 3, v181
	v_add_u32_e32 v198, 2, v181
	v_add_u32_e32 v199, 1, v181
	s_add_i32 s11, s11, 1
	s_add_i32 s12, s12, 32
	v_add_u32_e32 v164, 32, v164
	s_cmp_gt_i32 s11, 3
	s_waitcnt vmcnt(5)
	v_mfma_f32_32x32x16_bf16 v[66:81], v[66:69], v[82:85], 0
	v_mfma_f32_32x32x16_bf16 v[66:81], v[114:117], v[86:89], v[66:81]
	v_mfma_f32_32x32x16_bf16 v[66:81], v[118:121], v[90:93], v[66:81]
	v_mfma_f32_32x32x16_bf16 v[66:81], v[200:203], v[94:97], v[66:81]
	v_mfma_f32_32x32x16_bf16 v[66:81], v[204:207], v[98:101], v[66:81]
	v_mfma_f32_32x32x16_bf16 v[66:81], v[208:211], v[102:105], v[66:81]
	v_mfma_f32_32x32x16_bf16 v[66:81], v[212:215], v[106:109], v[66:81]
	global_load_dwordx4 v[114:117], v[168:169], off offset:3872
	v_mfma_f32_32x32x16_bf16 v[66:81], v[184:187], v[110:113], v[66:81]
	s_nop 11
	v_mov_b32_e32 v158, v66
	v_pk_mul_f32 v[168:169], v[158:159], v[166:167]
	v_cvt_f32_i32_e32 v167, v171
	v_mov_b32_e32 v158, v67
	v_sub_f32_e32 v66, v168, v169
	v_cndmask_b32_e32 v165, v248, v66, vcc
	v_pk_mul_f32 v[66:67], v[158:159], v[166:167]
	v_cvt_f32_i32_e32 v167, v183
	v_mov_b32_e32 v158, v68
	v_sub_f32_e32 v66, v66, v67
	v_cmp_gt_u32_e32 vcc, s69, v171
	s_nop 1
	v_cndmask_b32_e32 v68, v248, v66, vcc
	v_pk_mul_f32 v[66:67], v[158:159], v[166:167]
	v_cvt_f32_i32_e32 v167, v188
	v_mov_b32_e32 v158, v69
	v_sub_f32_e32 v66, v66, v67
	v_cmp_gt_u32_e32 vcc, s69, v183
	v_max3_f32 v168, v165, s54, v68
	s_nop 0
	v_cndmask_b32_e32 v69, v248, v66, vcc
	v_pk_mul_f32 v[66:67], v[158:159], v[166:167]
	v_cvt_f32_i32_e32 v167, v189
	v_mov_b32_e32 v158, v70
	v_sub_f32_e32 v66, v66, v67
	v_cmp_gt_u32_e32 vcc, s69, v188
	s_nop 1
	v_cndmask_b32_e32 v70, v248, v66, vcc
	v_pk_mul_f32 v[66:67], v[158:159], v[166:167]
	v_cvt_f32_i32_e32 v167, v190
	v_mov_b32_e32 v158, v71
	v_sub_f32_e32 v66, v66, v67
	v_cmp_gt_u32_e32 vcc, s69, v189
	v_max3_f32 v168, v168, v69, v70
	s_nop 0
	v_cndmask_b32_e32 v71, v248, v66, vcc
	v_pk_mul_f32 v[66:67], v[158:159], v[166:167]
	v_cvt_f32_i32_e32 v167, v191
	v_mov_b32_e32 v158, v72
	v_sub_f32_e32 v66, v66, v67
	v_cmp_gt_u32_e32 vcc, s69, v190
	s_nop 1
	v_cndmask_b32_e32 v72, v248, v66, vcc
	v_pk_mul_f32 v[66:67], v[158:159], v[166:167]
	v_cvt_f32_i32_e32 v167, v192
	v_mov_b32_e32 v158, v73
	v_sub_f32_e32 v66, v66, v67
	v_cmp_gt_u32_e32 vcc, s69, v191
	v_max3_f32 v168, v168, v71, v72
	s_nop 0
	v_cndmask_b32_e32 v73, v248, v66, vcc
	v_pk_mul_f32 v[66:67], v[158:159], v[166:167]
	v_cvt_f32_i32_e32 v167, v193
	v_mov_b32_e32 v158, v74
	v_sub_f32_e32 v66, v66, v67
	v_cmp_gt_u32_e32 vcc, s69, v192
	s_nop 1
	v_cndmask_b32_e32 v74, v248, v66, vcc
	v_pk_mul_f32 v[66:67], v[158:159], v[166:167]
	v_cvt_f32_i32_e32 v167, v194
	v_mov_b32_e32 v158, v75
	v_sub_f32_e32 v66, v66, v67
	v_cmp_gt_u32_e32 vcc, s69, v193
	v_max3_f32 v168, v168, v73, v74
	s_nop 0
	v_cndmask_b32_e32 v75, v248, v66, vcc
	v_pk_mul_f32 v[66:67], v[158:159], v[166:167]
	v_cvt_f32_i32_e32 v167, v195
	v_mov_b32_e32 v158, v76
	v_sub_f32_e32 v66, v66, v67
	v_cmp_gt_u32_e32 vcc, s69, v194
	s_nop 1
	v_cndmask_b32_e32 v76, v248, v66, vcc
	v_pk_mul_f32 v[66:67], v[158:159], v[166:167]
	v_cvt_f32_i32_e32 v167, v196
	v_mov_b32_e32 v158, v77
	v_sub_f32_e32 v66, v66, v67
	v_cmp_gt_u32_e32 vcc, s69, v195
	v_max3_f32 v168, v168, v75, v76
	s_nop 0
	v_cndmask_b32_e32 v77, v248, v66, vcc
	v_pk_mul_f32 v[66:67], v[158:159], v[166:167]
	v_cvt_f32_i32_e32 v167, v197
	v_mov_b32_e32 v158, v78
	v_sub_f32_e32 v66, v66, v67
	v_cmp_gt_u32_e32 vcc, s69, v196
	s_nop 1
	v_cndmask_b32_e32 v78, v248, v66, vcc
	v_pk_mul_f32 v[66:67], v[158:159], v[166:167]
	v_cvt_f32_i32_e32 v167, v198
	v_mov_b32_e32 v158, v79
	v_sub_f32_e32 v66, v66, v67
	v_cmp_gt_u32_e32 vcc, s69, v197
	v_max3_f32 v168, v168, v77, v78
	s_nop 0
	v_cndmask_b32_e32 v79, v248, v66, vcc
	v_pk_mul_f32 v[66:67], v[158:159], v[166:167]
	v_cvt_f32_i32_e32 v167, v199
	v_mov_b32_e32 v158, v80
	v_sub_f32_e32 v66, v66, v67
	v_cmp_gt_u32_e32 vcc, s69, v198
	s_nop 1
	v_cndmask_b32_e32 v80, v248, v66, vcc
	v_pk_mul_f32 v[66:67], v[158:159], v[166:167]
	v_cvt_f32_i32_e32 v167, v181
	v_mov_b32_e32 v158, v81
	v_sub_f32_e32 v66, v66, v67
	v_cmp_gt_u32_e32 vcc, s69, v199
	v_max3_f32 v168, v168, v79, v80
	s_nop 0
	v_cndmask_b32_e32 v81, v248, v66, vcc
	v_pk_mul_f32 v[66:67], v[158:159], v[166:167]
	v_cmp_gt_u32_e32 vcc, s69, v181
	v_sub_f32_e32 v66, v66, v67
	v_subrev_u32_e32 v181, 32, v181
	v_cndmask_b32_e32 v66, v248, v66, vcc
	v_max3_f32 v67, v168, v81, v66
	v_mov_b32_e32 v158, v67
	s_nop 1
	v_permlane32_swap_b32_e32 v67, v158
	s_waitcnt lgkmcnt(0)
; DI float fexp2(float x) { return __builtin_amdgcn_exp2f(x); }
; #define MFMA32(a, b, c) __builtin_amdgcn_mfma_f32_32x32x16_bf16((a), (b), (c), 0, 0, 0)
; DI void dil_attn_phase(int wv, const bf16_t* qk, const bf16_t* vt, float* oacc, float* stats, bf16_t* ob, int g, int dil) {
;     ...
;             const float mn = fmaxf(m, mx), alpha = fexp2(m - mn); m = mn;
;             float ps = 0.f; f32x16 P;
; #pragma unroll
;             for (int i = 0; i < 16; ++i) { const float pv = fexp2(sv[i] - mn); P[i] = pv; ps += pv; }
;             l = l * alpha + ps;
; #pragma unroll
;             for (int d = 0; d < 4; ++d) O[d] = O[d] * alpha;
;             const bf16x8 pf0 = pack8(P, 0), pf1 = pack8(P, 1);
; #pragma unroll
;             for (int d = 0; d < 4; ++d) { O[d] = MFMA32(vf[d][0], pf0, O[d]); O[d] = MFMA32(vf[d][1], pf1, O[d]); }
;         }
	v_max3_f32 v67, v182, v67, v158
	v_sub_f32_e32 v158, v182, v67
	v_sub_f32_e32 v165, v165, v67
	v_sub_f32_e32 v68, v68, v67
	v_sub_f32_e32 v69, v69, v67
	v_sub_f32_e32 v70, v70, v67
	v_sub_f32_e32 v71, v71, v67
	v_sub_f32_e32 v72, v72, v67
	v_sub_f32_e32 v73, v73, v67
	v_sub_f32_e32 v74, v74, v67
	v_sub_f32_e32 v167, v66, v67
	v_exp_f32_e32 v165, v165
	v_exp_f32_e32 v168, v68
	v_exp_f32_e32 v169, v69
	v_exp_f32_e32 v170, v70
	v_exp_f32_e32 v171, v71
	v_exp_f32_e32 v72, v72
	v_exp_f32_e32 v73, v73
	v_exp_f32_e32 v74, v74
	v_exp_f32_e32 v66, v158
	v_cvt_pk_bf16_f32 v68, v165, v168
	v_cvt_pk_bf16_f32 v69, v169, v170
	v_cvt_pk_bf16_f32 v70, v171, v72
	v_pk_mul_f32 v[48:49], v[48:49], v[66:67] op_sel_hi:[1,0]
	v_pk_mul_f32 v[46:47], v[46:47], v[66:67] op_sel_hi:[1,0]
	v_pk_mul_f32 v[44:45], v[44:45], v[66:67] op_sel_hi:[1,0]
	v_cvt_pk_bf16_f32 v71, v73, v74
	v_pk_mul_f32 v[42:43], v[42:43], v[66:67] op_sel_hi:[1,0]
	v_pk_mul_f32 v[40:41], v[40:41], v[66:67] op_sel_hi:[1,0]
	v_pk_mul_f32 v[38:39], v[38:39], v[66:67] op_sel_hi:[1,0]
	v_pk_mul_f32 v[36:37], v[36:37], v[66:67] op_sel_hi:[1,0]
	v_pk_mul_f32 v[34:35], v[34:35], v[66:67] op_sel_hi:[1,0]
	v_sub_f32_e32 v75, v75, v67
	v_sub_f32_e32 v76, v76, v67
	s_waitcnt vmcnt(5)
	v_mfma_f32_32x32x16_bf16 v[34:49], v[142:145], v[68:71], v[34:49]
	v_sub_f32_e32 v77, v77, v67
	v_sub_f32_e32 v78, v78, v67
	v_sub_f32_e32 v79, v79, v67
	v_sub_f32_e32 v80, v80, v67
	v_sub_f32_e32 v81, v81, v67
	v_pk_mul_f32 v[64:65], v[64:65], v[66:67] op_sel_hi:[1,0]
	v_pk_mul_f32 v[62:63], v[62:63], v[66:67] op_sel_hi:[1,0]
	v_pk_mul_f32 v[60:61], v[60:61], v[66:67] op_sel_hi:[1,0]
	v_pk_mul_f32 v[58:59], v[58:59], v[66:67] op_sel_hi:[1,0]
	v_pk_mul_f32 v[56:57], v[56:57], v[66:67] op_sel_hi:[1,0]
	v_pk_mul_f32 v[54:55], v[54:55], v[66:67] op_sel_hi:[1,0]
	v_pk_mul_f32 v[52:53], v[52:53], v[66:67] op_sel_hi:[1,0]
	v_pk_mul_f32 v[50:51], v[50:51], v[66:67] op_sel_hi:[1,0]
	v_pk_mul_f32 v[32:33], v[32:33], v[66:67] op_sel_hi:[1,0]
	v_pk_mul_f32 v[30:31], v[30:31], v[66:67] op_sel_hi:[1,0]
	v_pk_mul_f32 v[28:29], v[28:29], v[66:67] op_sel_hi:[1,0]
	v_pk_mul_f32 v[26:27], v[26:27], v[66:67] op_sel_hi:[1,0]
	v_pk_mul_f32 v[24:25], v[24:25], v[66:67] op_sel_hi:[1,0]
	v_pk_mul_f32 v[22:23], v[22:23], v[66:67] op_sel_hi:[1,0]
	v_pk_mul_f32 v[20:21], v[20:21], v[66:67] op_sel_hi:[1,0]
	v_pk_mul_f32 v[18:19], v[18:19], v[66:67] op_sel_hi:[1,0]
	v_exp_f32_e32 v75, v75
	v_exp_f32_e32 v76, v76
	v_exp_f32_e32 v77, v77
	v_exp_f32_e32 v78, v78
	v_exp_f32_e32 v79, v79
	v_mfma_f32_32x32x16_bf16 v[50:65], v[130:133], v[68:71], v[50:65]
	v_exp_f32_e32 v80, v80
	v_exp_f32_e32 v81, v81
	v_exp_f32_e32 v130, v167
	v_pk_mul_f32 v[16:17], v[16:17], v[66:67] op_sel_hi:[1,0]
	v_pk_mul_f32 v[14:15], v[14:15], v[66:67] op_sel_hi:[1,0]
	v_pk_mul_f32 v[12:13], v[12:13], v[66:67] op_sel_hi:[1,0]
	v_pk_mul_f32 v[10:11], v[10:11], v[66:67] op_sel_hi:[1,0]
	s_waitcnt vmcnt(3)
	v_mfma_f32_32x32x16_bf16 v[18:33], v[138:141], v[68:71], v[18:33]
	v_mul_f32_e64 v8, v8, v66
	v_mul_f32_e64 v9, v9, v66
	v_mul_f32_e64 v6, v6, v66
	v_mul_f32_e64 v7, v7, v66
	v_mul_f32_e64 v4, v4, v66
	v_mul_f32_e64 v5, v5, v66
	v_pk_mul_f32 v[2:3], v[2:3], v[66:67] op_sel_hi:[1,0]
	s_waitcnt vmcnt(1)
	s_nop 0
	v_mfma_f32_32x32x16_bf16 v[2:17], v[224:227], v[68:71], v[2:17]
	v_cvt_pk_bf16_f32 v68, v75, v76
	v_cvt_pk_bf16_f32 v69, v77, v78
	v_cvt_pk_bf16_f32 v70, v79, v80
	v_cvt_pk_bf16_f32 v71, v81, v130
	s_nop 1
	v_mfma_f32_32x32x16_bf16 v[34:49], v[216:219], v[68:71], v[34:49]
	v_add_f32_e32 v122, 0, v165
	v_add_f32_e32 v122, v168, v122
	v_add_f32_e32 v122, v169, v122
	v_mfma_f32_32x32x16_bf16 v[18:33], v[220:223], v[68:71], v[18:33]
	v_add_f32_e32 v118, v170, v122
	v_add_f32_e32 v118, v171, v118
	v_add_f32_e32 v72, v72, v118
	v_add_f32_e32 v72, v73, v72
	v_add_f32_e32 v72, v74, v72
	v_add_f32_e32 v72, v75, v72
	v_add_f32_e32 v72, v76, v72
	v_mfma_f32_32x32x16_bf16 v[50:65], v[126:129], v[68:71], v[50:65]
	v_mov_b32_e32 v126, v180
	s_waitcnt vmcnt(0)
	v_mfma_f32_32x32x16_bf16 v[2:17], v[114:117], v[68:71], v[2:17]
	v_add_f32_e32 v68, v77, v72
	v_add_f32_e32 v68, v78, v68
	v_add_f32_e32 v68, v79, v68
	v_add_f32_e32 v68, v80, v68
	v_add_f32_e32 v68, v81, v68
	v_add_f32_e32 v180, v130, v68
	v_fmac_f32_e32 v180, v126, v66
	s_cbranch_scc0 .LBB0_281

; #define LAS __attribute__((address_space(3)))
; DI float fexp2(float x) { return __builtin_amdgcn_exp2f(x); }
; DI f32x16 zero16() { f32x16 z; for (int i = 0; i < 16; ++i) z[i] = 0.f; return z; }
; DI void diff_attn_phase(int wv, LAS unsigned char* lds, const bf16_t* qk, const bf16_t* vt, bf16_t* ob, const float* lq1, const float* lk1, const float* lq2, const float* lk2,
;                         const float* subg, int layer_idx) {
;     ...
;         for (int t = 0; t < tmain; ++t) {
;             const int key0 = t * 64;
;             const bool more = true;
;             if (more) {
; #pragma unroll
;                 for (int i = 0; i < 2; ++i) gk[i] = *(const u32x4*)(kg + (size_t)(key0 + 64 + i * 32) * 2048); }
;             LAS unsigned char* buf = lds + (t & 1) * DA_BUF;
;             {
;                 f32x16 S0 = zero16(), S1 = zero16();
;                 {
;                     bf16x8 kf[2][4];
; #pragma unroll
;                     for (int sub = 0; sub < 2; ++sub)
; #pragma unroll
;                         for (int ks = 0; ks < 4; ++ks) kf[sub][ks] = *(const LAS bf16x8*)(buf + koff + sub * 32 * DA_KP + ks * 32);
; #pragma unroll
;                     for (int ks = 0; ks < 4; ++ks) { const bf16x8 qfr = *(const LAS bf16x8*)(qlds + ks * 1024); S0 = MFMA32(kf[0][ks], qfr, S0); S1 = MFMA32(kf[1][ks], qfr, S1); }
;                 }
;                 __builtin_amdgcn_sched_barrier(0);
; #pragma unroll
;                 for (int i = 0; i < 2; ++i) gv[i] = *(const u32x4*)(vg + (size_t)i * 64 * M_TOK + key0 + 64);
;                 bf16x8 vf[4][2];
; #pragma unroll
;                 for (int d = 0; d < 4; ++d)
; #pragma unroll
;                     for (int s2 = 0; s2 < 2; ++s2) vf[d][s2] = *(const LAS bf16x8*)(buf + voff + d * 32 * DA_VP + (16 * s2) * 2);
;                 const float base = slope2 * (float)(key0 + 8 * hh - qpos), b32 = 32.f * slope2;
; #pragma unroll
;                 for (int i = 0; i < 16; ++i) { S0[i] = S0[i] * c1 + cb[i]; S1[i] = S1[i] * c1 + cb[i]; }
;                 float mx = -INFINITY, mx1 = -INFINITY;
; #pragma unroll
;                 for (int i = 0; i < 16; ++i) { mx = fmaxf(mx, S0[i]); mx1 = fmaxf(mx1, S1[i]); }
;                 mx = fmaxf(mx, mx1 + b32) + base;
;                 mx = fmaxf(mx, __shfl_xor(mx, 32));
;                 {
;                     const float mn = fmaxf(m, mx), alpha = fexp2(m - mn); m = mn; l *= alpha;
.LBB0_424:
	s_add_i32 s14, s16, 64
	s_ashr_i32 s15, s14, 31
	s_lshl_b64 s[26:27], s[14:15], 12
	v_lshl_add_u64 v[66:67], v[114:115], 0, s[26:27]
	s_add_i32 s26, s16, 0x60
	s_ashr_i32 s27, s26, 31
	s_lshl_b64 s[26:27], s[26:27], 12
	global_load_dwordx4 v[98:101], v[66:67], off offset:2048
	v_lshl_add_u64 v[66:67], v[114:115], 0, s[26:27]
	global_load_dwordx4 v[102:105], v[66:67], off offset:2048
	s_bitcmp1_b32 s25, 0
	s_cselect_b32 s2, 0x8c00, 0
	s_add_i32 s2, s2, 0
	v_add_u32_e32 v70, s2, v153
	ds_read_b128 v[66:69], v70
	ds_read_b128 v[82:85], v70 offset:32
	ds_read_b128 v[86:89], v70 offset:64
	ds_read_b128 v[90:93], v70 offset:96
	ds_read_b128 v[94:97], v70 offset:8704
	ds_read_b128 v[106:109], v70 offset:8736
	ds_read_b128 v[110:113], v70 offset:8768
	ds_read_b128 v[122:125], v70 offset:8800
	ds_read_b128 v[126:129], v217
	ds_read_b128 v[130:133], v217 offset:1024
	ds_read_b128 v[134:137], v217 offset:2048
	ds_read_b128 v[138:141], v217 offset:3072
	v_mov_b32_e32 v121, v159
	v_mov_b32_e32 v0, v218
	s_waitcnt lgkmcnt(3)
	v_mfma_f32_32x32x16_bf16 v[66:81], v[66:69], v[126:129], 0
	s_ashr_i32 s17, s16, 31
	s_mov_b32 s3, 0x400000
	v_add_u32_e32 v118, s16, v120
	v_add_u32_e32 v191, s2, v211
	s_waitcnt lgkmcnt(2)
	v_mfma_f32_32x32x16_bf16 v[66:81], v[82:85], v[130:133], v[66:81]
	s_waitcnt lgkmcnt(1)
	v_mfma_f32_32x32x16_bf16 v[66:81], v[86:89], v[134:137], v[66:81]
	s_waitcnt lgkmcnt(0)
	v_mfma_f32_32x32x16_bf16 v[66:81], v[90:93], v[138:141], v[66:81]
	v_mfma_f32_32x32x16_bf16 v[82:97], v[94:97], v[126:129], 0
	s_nop 10
	v_fmamk_f32 v127, v66, 0x3e38aa3b, v192
	v_max_f32_e32 v66, 0xff800000, v127
	v_fmamk_f32 v129, v69, 0x3e38aa3b, v189
	v_fmamk_f32 v159, v74, 0x3e38aa3b, v182
	v_fmamk_f32 v193, v75, 0x3e38aa3b, v183
	v_fmamk_f32 v196, v76, 0x3e38aa3b, v180
	v_cvt_f32_i32_e32 v126, v118
	v_mfma_f32_32x32x16_bf16 v[82:97], v[106:109], v[130:133], v[82:97]
	v_lshl_add_u64 v[106:107], s[16:17], 1, v[116:117]
	v_add_co_u32_e32 v108, vcc, s3, v106
	v_fmamk_f32 v131, v70, 0x3e38aa3b, v186
	s_nop 0
	v_addc_co_u32_e32 v109, vcc, 0, v107, vcc
	v_fmamk_f32 v133, v71, 0x3e38aa3b, v187
	v_mfma_f32_32x32x16_bf16 v[82:97], v[110:113], v[134:137], v[82:97]
	global_load_dwordx4 v[110:113], v[106:107], off offset:128
	s_nop 0
	global_load_dwordx4 v[106:109], v[108:109], off offset:128
	v_fmamk_f32 v135, v72, 0x3e38aa3b, v184
	v_fmamk_f32 v137, v73, 0x3e38aa3b, v185
	v_fmamk_f32 v199, v77, 0x3e38aa3b, v181
	v_fmamk_f32 v200, v78, 0x3e38aa3b, v178
	v_fmamk_f32 v204, v79, 0x3e38aa3b, v179
	v_fmamk_f32 v207, v80, 0x3e38aa3b, v176
	v_mfma_f32_32x32x16_bf16 v[82:97], v[122:125], v[138:141], v[82:97]
	v_fmamk_f32 v123, v67, 0x3e38aa3b, v160
	v_fmamk_f32 v125, v68, 0x3e38aa3b, v188
	v_max3_f32 v66, v66, v123, v125
	v_max3_f32 v66, v66, v129, v131
	v_max3_f32 v66, v66, v133, v135
	v_max3_f32 v66, v66, v137, v159
	v_max3_f32 v66, v66, v193, v196
	s_nop 4
	v_fmamk_f32 v122, v82, 0x3e38aa3b, v192
	v_fmamk_f32 v124, v83, 0x3e38aa3b, v160
	v_fmamk_f32 v128, v84, 0x3e38aa3b, v188
	v_fmamk_f32 v130, v85, 0x3e38aa3b, v189
	v_max3_f32 v67, v122, s54, v124
	v_fmamk_f32 v132, v86, 0x3e38aa3b, v186
	v_fmamk_f32 v134, v87, 0x3e38aa3b, v187
	v_max3_f32 v67, v67, v128, v130
	v_fmamk_f32 v136, v88, 0x3e38aa3b, v184
	v_fmamk_f32 v143, v89, 0x3e38aa3b, v185
	v_max3_f32 v67, v67, v132, v134
	v_fmamk_f32 v169, v90, 0x3e38aa3b, v182
	v_fmamk_f32 v195, v91, 0x3e38aa3b, v183
	v_max3_f32 v67, v67, v136, v143
	v_fmamk_f32 v198, v92, 0x3e38aa3b, v180
	v_fmamk_f32 v202, v93, 0x3e38aa3b, v181
	v_max3_f32 v67, v67, v169, v195
	v_fmamk_f32 v203, v94, 0x3e38aa3b, v178
	v_fmamk_f32 v206, v95, 0x3e38aa3b, v179
	v_max3_f32 v67, v67, v198, v202
	v_fmamk_f32 v219, v96, 0x3e38aa3b, v176
	v_fmamk_f32 v222, v97, 0x3e38aa3b, v177
	v_max3_f32 v67, v67, v203, v206
	v_max3_f32 v66, v66, v199, v200
	v_max3_f32 v67, v67, v219, v222
	v_fmamk_f32 v220, v81, 0x3e38aa3b, v177
	v_max3_f32 v66, v66, v204, v207
	v_add_f32_e32 v67, v157, v67
	v_max3_f32 v66, v66, v220, v67
	v_fmac_f32_e32 v66, v160, v126
	v_mov_b32_e32 v67, v66
	s_nop 1
	v_permlane32_swap_b32_e32 v66, v67
	ds_read_b128 v[94:97], v191 offset:17408
	ds_read_b128 v[90:93], v191 offset:17440
	ds_read_b128 v[86:89], v191 offset:22016
	ds_read_b128 v[82:85], v191 offset:22048
	s_waitcnt lgkmcnt(4)
; DI float fexp2(float x) { return __builtin_amdgcn_exp2f(x); }
; DI void diff_attn_phase(int wv, LAS unsigned char* lds, const bf16_t* qk, const bf16_t* vt, bf16_t* ob, const float* lq1, const float* lk1, const float* lq2, const float* lk2,
;                         const float* subg, int layer_idx) {
;     ...
;                     const float mn = fmaxf(m, mx), alpha = fexp2(m - mn); m = mn; l *= alpha;
; #pragma unroll
;                     for (int d = 0; d < 4; ++d) O[d] = O[d] * alpha;
;                 }
;                 const float off = base - m, off1 = off + b32;
;                 float ps = 0.f;
; #pragma unroll
;                 for (int i = 0; i < 16; ++i) { S0[i] = fexp2(S0[i] + off); S1[i] = fexp2(S1[i] + off1); ps += S0[i] + S1[i]; }
;                 l += ps;
;                 const bf16x8 p0 = pack8(S0, 0), p1 = pack8(S0, 1), p2 = pack8(S1, 0), p3 = pack8(S1, 1);
	v_max3_f32 v218, v0, v66, v67
	v_sub_f32_e32 v0, v0, v218
	v_fma_f32 v126, v160, v126, -v218
	v_exp_f32_e32 v118, v0
	v_add_f32_e32 v223, v157, v126
	v_add_f32_e32 v0, v127, v126
	v_exp_f32_e32 v127, v0
	v_add_f32_e32 v0, v122, v223
	v_add_f32_e32 v122, v125, v126
	v_exp_f32_e32 v224, v0
	v_add_f32_e32 v0, v123, v126
	v_exp_f32_e32 v123, v122
	v_add_f32_e32 v122, v128, v223
	v_exp_f32_e32 v225, v122
	v_add_f32_e32 v122, v129, v126
	v_exp_f32_e32 v140, v122
	v_add_f32_e32 v122, v130, v223
	v_exp_f32_e32 v142, v122
	v_add_f32_e32 v122, v133, v126
	v_exp_f32_e32 v144, v122
	v_add_f32_e32 v122, v134, v223
	v_exp_f32_e32 v168, v122
	v_add_f32_e32 v122, v137, v126
	v_exp_f32_e32 v170, v122
	v_add_f32_e32 v122, v143, v223
	v_add_f32_e32 v129, v169, v223
	v_exp_f32_e32 v194, v122
	v_add_f32_e32 v122, v193, v126
	v_exp_f32_e32 v134, v129
	v_add_f32_e32 v129, v196, v126
	v_exp_f32_e32 v196, v122
	v_add_f32_e32 v122, v195, v223
	v_add_f32_e32 v125, v132, v223
	v_add_f32_e32 v130, v198, v223
	v_exp_f32_e32 v198, v122
	v_add_f32_e32 v122, v199, v126
	v_exp_f32_e32 v132, v125
	v_add_f32_e32 v125, v135, v126
	v_exp_f32_e32 v135, v130
	v_add_f32_e32 v130, v200, v126
	v_exp_f32_e32 v200, v122
	v_add_f32_e32 v122, v202, v223
	v_exp_f32_e32 v202, v122
	v_add_f32_e32 v122, v204, v126
	ds_read_b128 v[78:81], v191 offset:26624
	ds_read_b128 v[74:77], v191 offset:26656
	ds_read_b128 v[70:73], v191 offset:31232
	ds_read_b128 v[66:69], v191 offset:31264
	v_exp_f32_e32 v204, v122
	v_add_f32_e32 v122, v206, v223
	v_exp_f32_e32 v138, v0
	v_add_f32_e32 v0, v124, v223
	v_add_f32_e32 v124, v131, v126
	v_add_f32_e32 v128, v136, v223
	v_add_f32_e32 v131, v203, v223
	v_exp_f32_e32 v206, v122
	v_add_f32_e32 v122, v220, v126
	v_exp_f32_e32 v133, v128
	v_add_f32_e32 v128, v159, v126
	v_exp_f32_e32 v136, v131
	v_add_f32_e32 v131, v207, v126
	v_add_f32_e32 v137, v219, v223
	v_exp_f32_e32 v220, v122
	v_add_f32_e32 v122, v222, v223
	v_exp_f32_e32 v0, v0
	v_exp_f32_e32 v124, v124
	v_exp_f32_e32 v125, v125
	v_exp_f32_e32 v128, v128
	v_exp_f32_e32 v129, v129
	v_exp_f32_e32 v130, v130
	v_exp_f32_e32 v131, v131
	v_exp_f32_e32 v137, v137
	v_exp_f32_e32 v222, v122
	v_pk_mul_f32 v[64:65], v[64:65], v[118:119] op_sel_hi:[1,0]
	v_pk_mul_f32 v[62:63], v[62:63], v[118:119] op_sel_hi:[1,0]
	v_pk_mul_f32 v[60:61], v[60:61], v[118:119] op_sel_hi:[1,0]
	v_pk_mul_f32 v[58:59], v[58:59], v[118:119] op_sel_hi:[1,0]
	v_pk_mul_f32 v[56:57], v[56:57], v[118:119] op_sel_hi:[1,0]
	v_pk_mul_f32 v[54:55], v[54:55], v[118:119] op_sel_hi:[1,0]
	v_pk_mul_f32 v[52:53], v[52:53], v[118:119] op_sel_hi:[1,0]
	v_pk_mul_f32 v[50:51], v[50:51], v[118:119] op_sel_hi:[1,0]
	v_pk_mul_f32 v[48:49], v[48:49], v[118:119] op_sel_hi:[1,0]
	v_pk_mul_f32 v[46:47], v[46:47], v[118:119] op_sel_hi:[1,0]
	v_pk_mul_f32 v[44:45], v[44:45], v[118:119] op_sel_hi:[1,0]
	v_pk_mul_f32 v[42:43], v[42:43], v[118:119] op_sel_hi:[1,0]
	v_pk_mul_f32 v[40:41], v[40:41], v[118:119] op_sel_hi:[1,0]
	v_pk_mul_f32 v[38:39], v[38:39], v[118:119] op_sel_hi:[1,0]
	v_pk_mul_f32 v[36:37], v[36:37], v[118:119] op_sel_hi:[1,0]
	v_pk_mul_f32 v[34:35], v[34:35], v[118:119] op_sel_hi:[1,0]
	v_pk_mul_f32 v[32:33], v[32:33], v[118:119] op_sel_hi:[1,0]
	v_pk_mul_f32 v[30:31], v[30:31], v[118:119] op_sel_hi:[1,0]
	v_pk_mul_f32 v[28:29], v[28:29], v[118:119] op_sel_hi:[1,0]
	v_pk_mul_f32 v[26:27], v[26:27], v[118:119] op_sel_hi:[1,0]
	v_pk_mul_f32 v[24:25], v[24:25], v[118:119] op_sel_hi:[1,0]
	v_pk_mul_f32 v[22:23], v[22:23], v[118:119] op_sel_hi:[1,0]
	v_pk_mul_f32 v[20:21], v[20:21], v[118:119] op_sel_hi:[1,0]
	v_pk_mul_f32 v[18:19], v[18:19], v[118:119] op_sel_hi:[1,0]
	v_pk_mul_f32 v[16:17], v[16:17], v[118:119] op_sel_hi:[1,0]
	v_pk_mul_f32 v[14:15], v[14:15], v[118:119] op_sel_hi:[1,0]
	v_pk_mul_f32 v[12:13], v[12:13], v[118:119] op_sel_hi:[1,0]
	v_pk_mul_f32 v[10:11], v[10:11], v[118:119] op_sel_hi:[1,0]
	v_pk_mul_f32 v[8:9], v[8:9], v[118:119] op_sel_hi:[1,0]
	v_pk_mul_f32 v[6:7], v[6:7], v[118:119] op_sel_hi:[1,0]
	v_pk_mul_f32 v[4:5], v[4:5], v[118:119] op_sel_hi:[1,0]
	v_pk_mul_f32 v[2:3], v[2:3], v[118:119] op_sel_hi:[1,0]
	v_add_f32_e32 v139, v127, v224
	v_add_f32_e32 v141, v123, v225
	v_add_f32_e32 v145, v124, v132
	v_add_f32_e32 v171, v125, v133
	v_add_f32_e32 v197, v128, v134
	v_add_f32_e32 v201, v129, v135
	v_add_f32_e32 v205, v130, v136
	v_add_f32_e32 v221, v131, v137
	v_cvt_pk_bf16_f32 v122, v127, v138
	v_cvt_pk_bf16_f32 v123, v123, v140
	v_cvt_pk_bf16_f32 v124, v124, v144
	v_cvt_pk_bf16_f32 v125, v125, v170
	v_cvt_pk_bf16_f32 v126, v128, v196
	v_cvt_pk_bf16_f32 v127, v129, v200
	v_cvt_pk_bf16_f32 v128, v130, v204
	v_cvt_pk_bf16_f32 v129, v131, v220
	v_cvt_pk_bf16_f32 v130, v224, v0
	v_cvt_pk_bf16_f32 v131, v225, v142
	v_cvt_pk_bf16_f32 v132, v132, v168
	v_cvt_pk_bf16_f32 v133, v133, v194
	v_cvt_pk_bf16_f32 v134, v134, v198
	v_cvt_pk_bf16_f32 v135, v135, v202
	v_cvt_pk_bf16_f32 v136, v136, v206
	v_cvt_pk_bf16_f32 v137, v137, v222
	s_waitcnt lgkmcnt(5)
; #define LAS __attribute__((address_space(3)))
; #define MFMA32(a, b, c) __builtin_amdgcn_mfma_f32_32x32x16_bf16((a), (b), (c), 0, 0, 0)
; DI void diff_attn_phase(int wv, LAS unsigned char* lds, const bf16_t* qk, const bf16_t* vt, bf16_t* ob, const float* lq1, const float* lk1, const float* lq2, const float* lk2,
;                         const float* subg, int layer_idx) {
;     ...
;                 const bf16x8 p0 = pack8(S0, 0), p1 = pack8(S0, 1), p2 = pack8(S1, 0), p3 = pack8(S1, 1);
;                 __builtin_amdgcn_sched_barrier(0);
; #pragma unroll
;                 for (int d = 0; d < 4; ++d) { O[d] = MFMA32(vf[d][0], p0, O[d]); O[d] = MFMA32(vf[d][1], p1, O[d]); }
;                 __builtin_amdgcn_sched_barrier(0);
; #pragma unroll
;                 for (int d = 0; d < 4; ++d)
; #pragma unroll
;                     for (int s2 = 0; s2 < 2; ++s2) vf[d][s2] = *(const LAS bf16x8*)(buf + voff + d * 32 * DA_VP + (32 + 16 * s2) * 2);
; #pragma unroll
;                 for (int d = 0; d < 4; ++d) { O[d] = MFMA32(vf[d][0], p2, O[d]); O[d] = MFMA32(vf[d][1], p3, O[d]); }
;             }
;             if (more) {
;                 LAS unsigned char* nb = lds + ((t + 1) & 1) * DA_BUF;
; #pragma unroll
;                 for (int i = 0; i < 2; ++i) { *(LAS u32x4*)(nb + kst_off + i * 32 * DA_KP) = gk[i]; *(LAS u32x4*)(nb + vst_off + i * 64 * DA_VP) = gv[i]; } }
;             __syncthreads();
	v_mfma_f32_32x32x16_bf16 v[34:49], v[86:89], v[122:125], v[34:49]
	s_waitcnt lgkmcnt(4)
	v_mfma_f32_32x32x16_bf16 v[34:49], v[82:85], v[126:129], v[34:49]
	v_add_f32_e64 v82, v138, v0
	v_add_f32_e64 v83, v139, v1
	s_waitcnt lgkmcnt(3)
	v_mfma_f32_32x32x16_bf16 v[18:33], v[78:81], v[122:125], v[18:33]
	v_add_f32_e64 v78, v82, v82
	v_add_f32_e64 v79, v82, v83
	v_mov_b32_e32 v143, v79
	v_add_f32_e64 v78, v140, v142
	v_add_f32_e64 v79, v141, v143
	v_pk_add_f32 v[78:79], v[78:79], v[78:79] op_sel_hi:[0,1]
	v_mov_b32_e32 v169, v79
	v_pk_add_f32 v[78:79], v[144:145], v[168:169]
	v_mfma_f32_32x32x16_bf16 v[50:65], v[94:97], v[122:125], v[50:65]
	v_pk_add_f32 v[78:79], v[78:79], v[78:79] op_sel_hi:[0,1]
	v_mov_b32_e32 v195, v79
	s_waitcnt lgkmcnt(1)
	v_mfma_f32_32x32x16_bf16 v[2:17], v[70:73], v[122:125], v[2:17]
	v_mfma_f32_32x32x16_bf16 v[18:33], v[74:77], v[126:129], v[18:33]
	v_add_f32_e64 v74, v170, v194
	v_add_f32_e64 v75, v171, v195
	v_pk_add_f32 v[74:75], v[74:75], v[74:75] op_sel_hi:[0,1]
	v_mov_b32_e32 v199, v75
	v_pk_add_f32 v[74:75], v[196:197], v[198:199]
	s_nop 0
	v_pk_add_f32 v[74:75], v[74:75], v[74:75] op_sel_hi:[0,1]
	v_mov_b32_e32 v203, v75
	v_mfma_f32_32x32x16_bf16 v[50:65], v[90:93], v[126:129], v[50:65]
	v_add_f32_e64 v70, v200, v202
	v_add_f32_e64 v71, v201, v203
	v_pk_add_f32 v[70:71], v[70:71], v[70:71] op_sel_hi:[0,1]
	v_mov_b32_e32 v207, v71
	v_pk_add_f32 v[70:71], v[204:205], v[206:207]
	s_nop 0
	v_pk_add_f32 v[70:71], v[70:71], v[70:71] op_sel_hi:[0,1]
	s_waitcnt lgkmcnt(0)
	v_mfma_f32_32x32x16_bf16 v[2:17], v[66:69], v[126:129], v[2:17]
	v_mov_b32_e32 v223, v71
	v_add_f32_e64 v70, v220, v222
	v_add_f32_e64 v71, v221, v223
	v_add_f32_e32 v159, v70, v71
	ds_read_b128 v[66:69], v191 offset:17472
	ds_read_b128 v[70:73], v191 offset:17504
	ds_read_b128 v[78:81], v191 offset:22080
	ds_read_b128 v[82:85], v191 offset:22112
	ds_read_b128 v[86:89], v191 offset:26688
	ds_read_b128 v[90:93], v191 offset:26720
	ds_read_b128 v[94:97], v191 offset:31296
	ds_read_b128 v[74:77], v191 offset:31328
	s_add_i32 s25, s25, 1
	s_bitcmp1_b32 s25, 0
	s_cselect_b32 s2, 0x8c00, 0
	s_add_i32 s2, s2, 0
	v_add_u32_e32 v0, s2, v167
	v_add_u32_e32 v223, s2, v208
	v_fmac_f32_e32 v159, v121, v118
	s_cmp_eq_u32 s1, s25
	s_mov_b32 s16, s14
	s_waitcnt vmcnt(3)
	ds_write_b128 v0, v[98:101]
	s_waitcnt vmcnt(1)
	ds_write_b128 v223, v[110:113] offset:17408
	ds_write_b128 v0, v[102:105] offset:8704
	s_waitcnt vmcnt(0)
	ds_write_b128 v223, v[106:109] offset:26624
	s_waitcnt lgkmcnt(11)
	v_mfma_f32_32x32x16_bf16 v[50:65], v[66:69], v[130:133], v[50:65]
	s_waitcnt lgkmcnt(10)
	v_mfma_f32_32x32x16_bf16 v[50:65], v[70:73], v[134:137], v[50:65]
	s_waitcnt lgkmcnt(9)
	v_mfma_f32_32x32x16_bf16 v[34:49], v[78:81], v[130:133], v[34:49]
	s_waitcnt lgkmcnt(8)
	v_mfma_f32_32x32x16_bf16 v[34:49], v[82:85], v[134:137], v[34:49]
	s_waitcnt lgkmcnt(7)
	v_mfma_f32_32x32x16_bf16 v[18:33], v[86:89], v[130:133], v[18:33]
	s_waitcnt lgkmcnt(6)
	v_mfma_f32_32x32x16_bf16 v[18:33], v[90:93], v[134:137], v[18:33]
	s_waitcnt lgkmcnt(5)
	v_mfma_f32_32x32x16_bf16 v[2:17], v[94:97], v[130:133], v[2:17]
	s_waitcnt lgkmcnt(0)
	s_barrier
	v_mfma_f32_32x32x16_bf16 v[2:17], v[74:77], v[134:137], v[2:17]
	s_cbranch_scc0 .LBB0_424
	s_branch .LBB0_427

; #define LAS __attribute__((address_space(3)))
; DI float fexp2(float x) { return __builtin_amdgcn_exp2f(x); }
; #define MFMA32(a, b, c) __builtin_amdgcn_mfma_f32_32x32x16_bf16((a), (b), (c), 0, 0, 0)
; DI void diff_attn_phase(int wv, LAS unsigned char* lds, const bf16_t* qk, const bf16_t* vt, bf16_t* ob, const float* lq1, const float* lk1, const float* lq2, const float* lk2,
;                         const float* subg, int layer_idx) {
;     ...
;                 float mx = -INFINITY, mx1 = -INFINITY;
; #pragma unroll
;                 for (int i = 0; i < 16; ++i) { mx = fmaxf(mx, S0[i]); mx1 = fmaxf(mx1, S1[i]); }
;                 mx = fmaxf(mx, mx1 + b32) + base;
;                 mx = fmaxf(mx, __shfl_xor(mx, 32));
;                 {
;                     const float mn = fmaxf(m, mx), alpha = fexp2(m - mn); m = mn; l *= alpha;
; #pragma unroll
;                     for (int d = 0; d < 4; ++d) O[d] = O[d] * alpha;
;                 }
;                 const float off = base - m, off1 = off + b32;
;                 float ps = 0.f;
; #pragma unroll
;                 for (int i = 0; i < 16; ++i) { S0[i] = fexp2(S0[i] + off); S1[i] = fexp2(S1[i] + off1); ps += S0[i] + S1[i]; }
;                 l += ps;
;                 const bf16x8 p0 = pack8(S0, 0), p1 = pack8(S0, 1), p2 = pack8(S1, 0), p3 = pack8(S1, 1);
;                 __builtin_amdgcn_sched_barrier(0);
; #pragma unroll
;                 for (int d = 0; d < 4; ++d) { O[d] = MFMA32(vf[d][0], p0, O[d]); O[d] = MFMA32(vf[d][1], p1, O[d]); }
;                 __builtin_amdgcn_sched_barrier(0);
; #pragma unroll
;                 for (int d = 0; d < 4; ++d)
; #pragma unroll
;                     for (int s2 = 0; s2 < 2; ++s2) vf[d][s2] = *(const LAS bf16x8*)(buf + voff + d * 32 * DA_VP + (32 + 16 * s2) * 2);
; #pragma unroll
;                 for (int d = 0; d < 4; ++d) { O[d] = MFMA32(vf[d][0], p2, O[d]); O[d] = MFMA32(vf[d][1], p3, O[d]); }
.LBB0_430:
	v_max_f32_e32 v76, v206, v206
	v_max3_f32 v77, v202, s54, v203
	v_max_f32_e32 v76, 0xff800000, v76
	v_max3_f32 v77, v77, v198, v199
	v_max3_f32 v76, v76, v207, v204
	v_max3_f32 v77, v77, v194, v195
	v_max3_f32 v76, v76, v205, v200
	v_max3_f32 v77, v77, v86, v87
	v_max3_f32 v76, v76, v201, v196
	v_max3_f32 v77, v77, v82, v83
	v_sub_u32_e32 v0, v0, v162
	v_max3_f32 v76, v76, v197, v88
	v_max3_f32 v77, v77, v70, v71
	v_cvt_f32_i32_e32 v0, v0
	v_max3_f32 v76, v76, v89, v84
	v_max3_f32 v77, v77, v66, v67
	v_max3_f32 v76, v76, v85, v72
	v_max3_f32 v77, v77, v74, v75
	v_max3_f32 v76, v76, v73, v68
	v_add_f32_e32 v77, v157, v77
	v_max3_f32 v76, v76, v69, v77
	v_fmac_f32_e32 v76, v160, v0
	v_mov_b32_e32 v77, v76
	s_nop 1
	v_permlane32_swap_b32_e32 v76, v77
	s_waitcnt lgkmcnt(0)
	v_max3_f32 v77, v218, v76, v77
	v_fma_f32 v78, v160, v0, -v77
	v_add_f32_e32 v79, v157, v78
	v_add_f32_e32 v86, v86, v79
	v_add_f32_e32 v88, v88, v78
	v_add_f32_e32 v87, v87, v79
	v_add_f32_e32 v70, v70, v79
	v_add_f32_e32 v0, v206, v78
	v_add_f32_e32 v94, v200, v78
	v_exp_f32_e32 v206, v86
	v_add_f32_e32 v86, v195, v79
	v_exp_f32_e32 v195, v88
	v_exp_f32_e32 v88, v87
	v_add_f32_e32 v87, v89, v78
	v_exp_f32_e32 v89, v70
	v_add_f32_e32 v70, v83, v79
	v_add_f32_e32 v66, v66, v79
	v_add_f32_e32 v90, v204, v78
	v_exp_f32_e32 v193, v94
	v_add_f32_e32 v94, v194, v79
	v_exp_f32_e32 v194, v70
	v_add_f32_e32 v70, v85, v78
	v_exp_f32_e32 v85, v66
	v_add_f32_e32 v66, v71, v79
	v_exp_f32_e32 v95, v90
	v_add_f32_e32 v90, v198, v79
	v_exp_f32_e32 v198, v66
	v_add_f32_e32 v66, v73, v78
	v_exp_f32_e32 v80, v0
	v_add_f32_e32 v0, v202, v79
	v_add_f32_e32 v68, v68, v78
	v_exp_f32_e32 v200, v66
	v_add_f32_e32 v66, v67, v79
	v_sub_f32_e32 v76, v218, v77
	v_exp_f32_e32 v81, v0
	v_add_f32_e32 v0, v207, v78
	v_add_f32_e32 v168, v196, v78
	v_exp_f32_e32 v73, v68
	v_add_f32_e32 v68, v74, v79
	v_exp_f32_e32 v74, v66
	v_add_f32_e32 v66, v69, v78
	v_exp_f32_e32 v76, v76
	v_exp_f32_e32 v191, v90
	v_exp_f32_e32 v90, v0
	v_add_f32_e32 v0, v203, v79
	v_add_f32_e32 v92, v205, v78
	v_exp_f32_e32 v205, v94
	v_add_f32_e32 v94, v199, v79
	v_add_f32_e32 v96, v201, v78
	v_exp_f32_e32 v199, v168
	v_add_f32_e32 v168, v197, v78
	v_add_f32_e32 v82, v82, v79
	v_add_f32_e32 v84, v84, v78
	v_add_f32_e32 v72, v72, v78
	v_exp_f32_e32 v202, v66
	v_add_f32_e32 v66, v75, v79
	v_exp_f32_e32 v0, v0
	v_exp_f32_e32 v92, v92
	v_exp_f32_e32 v94, v94
	v_exp_f32_e32 v96, v96
	v_exp_f32_e32 v86, v86
	v_exp_f32_e32 v82, v82
	v_exp_f32_e32 v168, v168
	v_exp_f32_e32 v84, v84
	v_exp_f32_e32 v170, v87
	v_exp_f32_e32 v72, v72
	v_exp_f32_e32 v196, v70
	v_exp_f32_e32 v87, v68
	v_exp_f32_e32 v204, v66
	v_pk_mul_f32 v[64:65], v[64:65], v[76:77] op_sel_hi:[1,0]
	v_pk_mul_f32 v[62:63], v[62:63], v[76:77] op_sel_hi:[1,0]
	v_pk_mul_f32 v[60:61], v[60:61], v[76:77] op_sel_hi:[1,0]
	v_pk_mul_f32 v[58:59], v[58:59], v[76:77] op_sel_hi:[1,0]
	v_pk_mul_f32 v[56:57], v[56:57], v[76:77] op_sel_hi:[1,0]
	v_pk_mul_f32 v[54:55], v[54:55], v[76:77] op_sel_hi:[1,0]
	v_pk_mul_f32 v[52:53], v[52:53], v[76:77] op_sel_hi:[1,0]
	v_pk_mul_f32 v[50:51], v[50:51], v[76:77] op_sel_hi:[1,0]
	v_pk_mul_f32 v[48:49], v[48:49], v[76:77] op_sel_hi:[1,0]
	v_pk_mul_f32 v[46:47], v[46:47], v[76:77] op_sel_hi:[1,0]
	v_pk_mul_f32 v[44:45], v[44:45], v[76:77] op_sel_hi:[1,0]
	v_pk_mul_f32 v[42:43], v[42:43], v[76:77] op_sel_hi:[1,0]
	v_pk_mul_f32 v[40:41], v[40:41], v[76:77] op_sel_hi:[1,0]
	v_pk_mul_f32 v[38:39], v[38:39], v[76:77] op_sel_hi:[1,0]
	v_pk_mul_f32 v[36:37], v[36:37], v[76:77] op_sel_hi:[1,0]
	v_pk_mul_f32 v[34:35], v[34:35], v[76:77] op_sel_hi:[1,0]
	v_pk_mul_f32 v[32:33], v[32:33], v[76:77] op_sel_hi:[1,0]
	v_pk_mul_f32 v[30:31], v[30:31], v[76:77] op_sel_hi:[1,0]
	v_pk_mul_f32 v[28:29], v[28:29], v[76:77] op_sel_hi:[1,0]
	v_pk_mul_f32 v[26:27], v[26:27], v[76:77] op_sel_hi:[1,0]
	v_pk_mul_f32 v[24:25], v[24:25], v[76:77] op_sel_hi:[1,0]
	v_pk_mul_f32 v[22:23], v[22:23], v[76:77] op_sel_hi:[1,0]
	v_pk_mul_f32 v[20:21], v[20:21], v[76:77] op_sel_hi:[1,0]
	v_pk_mul_f32 v[18:19], v[18:19], v[76:77] op_sel_hi:[1,0]
	v_pk_mul_f32 v[16:17], v[16:17], v[76:77] op_sel_hi:[1,0]
	v_pk_mul_f32 v[14:15], v[14:15], v[76:77] op_sel_hi:[1,0]
	v_pk_mul_f32 v[12:13], v[12:13], v[76:77] op_sel_hi:[1,0]
	v_pk_mul_f32 v[10:11], v[10:11], v[76:77] op_sel_hi:[1,0]
	v_pk_mul_f32 v[8:9], v[8:9], v[76:77] op_sel_hi:[1,0]
	v_pk_mul_f32 v[6:7], v[6:7], v[76:77] op_sel_hi:[1,0]
	v_pk_mul_f32 v[4:5], v[4:5], v[76:77] op_sel_hi:[1,0]
	v_pk_mul_f32 v[2:3], v[2:3], v[76:77] op_sel_hi:[1,0]
	v_add_f32_e32 v91, v80, v81
	v_add_f32_e32 v93, v95, v191
	v_add_f32_e32 v97, v193, v205
	v_add_f32_e32 v169, v199, v206
	v_add_f32_e32 v171, v195, v82
	v_add_f32_e32 v197, v84, v89
	v_add_f32_e32 v201, v72, v85
	v_add_f32_e32 v203, v73, v87
	v_cvt_pk_bf16_f32 v66, v80, v90
	v_cvt_pk_bf16_f32 v67, v95, v92
	v_cvt_pk_bf16_f32 v68, v193, v96
	v_cvt_pk_bf16_f32 v69, v199, v168
	v_cvt_pk_bf16_f32 v70, v195, v170
	v_cvt_pk_bf16_f32 v71, v84, v196
	v_cvt_pk_bf16_f32 v72, v72, v200
	v_cvt_pk_bf16_f32 v73, v73, v202
	v_cvt_pk_bf16_f32 v78, v81, v0
	v_cvt_pk_bf16_f32 v79, v191, v94
	v_cvt_pk_bf16_f32 v80, v205, v86
	v_cvt_pk_bf16_f32 v81, v206, v88
	v_cvt_pk_bf16_f32 v82, v82, v194
	v_cvt_pk_bf16_f32 v83, v89, v198
	v_cvt_pk_bf16_f32 v84, v85, v74
	v_cvt_pk_bf16_f32 v85, v87, v204
	v_pk_add_f32 v[90:91], v[90:91], v[0:1]
	v_mfma_f32_32x32x16_bf16 v[50:65], v[142:145], v[66:69], v[50:65]
	v_pk_add_f32 v[90:91], v[90:91], v[90:91] op_sel_hi:[0,1]
	v_mov_b32_e32 v95, v91
	v_pk_add_f32 v[90:91], v[92:93], v[94:95]
	s_nop 0
	v_pk_add_f32 v[90:91], v[90:91], v[90:91] op_sel_hi:[0,1]
	v_mov_b32_e32 v87, v91
	v_pk_add_f32 v[86:87], v[96:97], v[86:87]
	v_mfma_f32_32x32x16_bf16 v[34:49], v[134:137], v[66:69], v[34:49]
	v_pk_add_f32 v[86:87], v[86:87], v[86:87] op_sel_hi:[0,1]
	v_mov_b32_e32 v89, v87
	v_pk_add_f32 v[86:87], v[168:169], v[88:89]
	s_nop 0
	v_pk_add_f32 v[86:87], v[86:87], v[86:87] op_sel_hi:[0,1]
	v_mov_b32_e32 v195, v87
	v_pk_add_f32 v[86:87], v[170:171], v[194:195]
	v_mfma_f32_32x32x16_bf16 v[18:33], v[126:129], v[66:69], v[18:33]
	v_pk_add_f32 v[86:87], v[86:87], v[86:87] op_sel_hi:[0,1]
	v_mov_b32_e32 v199, v87
	v_mfma_f32_32x32x16_bf16 v[2:17], v[118:121], v[66:69], v[2:17]
	v_add_f32_e64 v66, v196, v198
	v_add_f32_e64 v67, v197, v199
	v_pk_add_f32 v[66:67], v[66:67], v[66:67] op_sel_hi:[0,1]
	v_mov_b32_e32 v75, v67
	v_pk_add_f32 v[66:67], v[200:201], v[74:75]
	s_nop 0
	v_pk_add_f32 v[66:67], v[66:67], v[66:67] op_sel_hi:[0,1]
	v_mfma_f32_32x32x16_bf16 v[50:65], v[138:141], v[70:73], v[50:65]
	v_mov_b32_e32 v205, v67
	v_add_f32_e64 v66, v202, v204
	v_add_f32_e64 v67, v203, v205
	v_add_f32_e32 v0, v66, v67
	v_mfma_f32_32x32x16_bf16 v[34:49], v[130:133], v[70:73], v[34:49]
	v_mfma_f32_32x32x16_bf16 v[18:33], v[122:125], v[70:73], v[18:33]
	v_mfma_f32_32x32x16_bf16 v[2:17], v[114:117], v[70:73], v[2:17]
	ds_read_b128 v[66:69], v212 offset:17472
	v_fmac_f32_e32 v0, v159, v76
	v_mov_b32_e32 v218, v77
	v_mov_b32_e32 v159, v0
	s_waitcnt lgkmcnt(0)
; #define LAS __attribute__((address_space(3)))
; #define MFMA32(a, b, c) __builtin_amdgcn_mfma_f32_32x32x16_bf16((a), (b), (c), 0, 0, 0)
; DI void diff_attn_phase(int wv, LAS unsigned char* lds, const bf16_t* qk, const bf16_t* vt, bf16_t* ob, const float* lq1, const float* lk1, const float* lq2, const float* lk2,
;                         const float* subg, int layer_idx) {
;     ...
; #pragma unroll
;                 for (int d = 0; d < 4; ++d)
; #pragma unroll
;                     for (int s2 = 0; s2 < 2; ++s2) vf[d][s2] = *(const LAS bf16x8*)(buf + voff + d * 32 * DA_VP + (32 + 16 * s2) * 2);
; #pragma unroll
;                 for (int d = 0; d < 4; ++d) { O[d] = MFMA32(vf[d][0], p2, O[d]); O[d] = MFMA32(vf[d][1], p3, O[d]); }
	v_mfma_f32_32x32x16_bf16 v[50:65], v[66:69], v[78:81], v[50:65]
	ds_read_b128 v[66:69], v212 offset:17504
	s_waitcnt lgkmcnt(0)
	v_mfma_f32_32x32x16_bf16 v[50:65], v[66:69], v[82:85], v[50:65]
	ds_read_b128 v[66:69], v212 offset:22080
	s_waitcnt lgkmcnt(0)
	v_mfma_f32_32x32x16_bf16 v[34:49], v[66:69], v[78:81], v[34:49]
	ds_read_b128 v[66:69], v212 offset:22112
	s_waitcnt lgkmcnt(0)
	v_mfma_f32_32x32x16_bf16 v[34:49], v[66:69], v[82:85], v[34:49]
	ds_read_b128 v[66:69], v212 offset:26688
	s_waitcnt lgkmcnt(0)
	v_mfma_f32_32x32x16_bf16 v[18:33], v[66:69], v[78:81], v[18:33]
	ds_read_b128 v[66:69], v212 offset:26720
	s_waitcnt lgkmcnt(0)
	v_mfma_f32_32x32x16_bf16 v[18:33], v[66:69], v[82:85], v[18:33]
	ds_read_b128 v[66:69], v212 offset:31296
	s_waitcnt lgkmcnt(0)
	v_mfma_f32_32x32x16_bf16 v[2:17], v[66:69], v[78:81], v[2:17]
	ds_read_b128 v[66:69], v212 offset:31328
	s_waitcnt lgkmcnt(0)
	v_mfma_f32_32x32x16_bf16 v[2:17], v[66:69], v[82:85], v[2:17]

; #define LAS __attribute__((address_space(3)))
; #define MFMA32(a, b, c) __builtin_amdgcn_mfma_f32_32x32x16_bf16((a), (b), (c), 0, 0, 0)
; DI f32x16 zero16() { f32x16 z; for (int i = 0; i < 16; ++i) z[i] = 0.f; return z; }
; DI void diff_attn_phase(int wv, LAS unsigned char* lds, const bf16_t* qk, const bf16_t* vt, bf16_t* ob, const float* lq1, const float* lk1, const float* lq2, const float* lk2,
;                         const float* subg, int layer_idx) {
;     ...
;             if (key0 <= q0 + 31) {
;                 f32x16 S0 = zero16(), S1 = zero16();
;                 {
;                     bf16x8 kf[2][4];
; #pragma unroll
;                     for (int sub = 0; sub < 2; ++sub)
; #pragma unroll
;                         for (int ks = 0; ks < 4; ++ks) kf[sub][ks] = *(const LAS bf16x8*)(buf + koff + sub * 32 * DA_KP + ks * 32);
; #pragma unroll
;                     for (int ks = 0; ks < 4; ++ks) { const bf16x8 qfr = *(const LAS bf16x8*)(qlds + ks * 1024); S0 = MFMA32(kf[0][ks], qfr, S0); S1 = MFMA32(kf[1][ks], qfr, S1); }
;                 }
;                 __builtin_amdgcn_sched_barrier(0);
;                 bf16x8 vf[4][2];
; #pragma unroll
;                 for (int d = 0; d < 4; ++d)
; #pragma unroll
;                     for (int s2 = 0; s2 < 2; ++s2) vf[d][s2] = *(const LAS bf16x8*)(buf + voff + d * 32 * DA_VP + (16 * s2) * 2);
;                 const float base = slope2 * (float)(key0 + 8 * hh - qpos), b32 = 32.f * slope2;
; #pragma unroll
;                 for (int i = 0; i < 16; ++i) { S0[i] = S0[i] * c1 + cb[i]; S1[i] = S1[i] * c1 + cb[i]; }
;                 if (key0 + 63 > q0) {
;                     const int kq = qpos - key0 - 8 * hh;
; #pragma unroll
;                     for (int i = 0; i < 16; ++i) { const int ko = (i & 7) + 16 * (i >> 3); S0[i] = (ko > kq) ? -INFINITY : S0[i]; S1[i] = (ko + 32 > kq) ? -INFINITY : S1[i]; }
;                 }
;                 float mx = -INFINITY, mx1 = -INFINITY;
; #pragma unroll
;                 for (int i = 0; i < 16; ++i) { mx = fmaxf(mx, S0[i]); mx1 = fmaxf(mx1, S1[i]); }
;                 mx = fmaxf(mx, mx1 + b32) + base;
;                 mx = fmaxf(mx, __shfl_xor(mx, 32));
.LBB0_433:
	s_cmp_gt_i32 s16, s1
	s_cbranch_scc1 .LBB0_435
	ds_read_b128 v[66:69], v219 offset:35840
	ds_read_b128 v[114:117], v219 offset:35872
	ds_read_b128 v[118:121], v219 offset:35904
	ds_read_b128 v[122:125], v219 offset:35936
	ds_read_b128 v[82:85], v219 offset:44544
	ds_read_b128 v[126:129], v219 offset:44576
	ds_read_b128 v[130:133], v219 offset:44608
	ds_read_b128 v[134:137], v219 offset:44640
	ds_read_b128 v[86:89], v217
	ds_read_b128 v[138:141], v217 offset:1024
	ds_read_b128 v[142:145], v217 offset:2048
	ds_read_b128 v[194:197], v217 offset:3072
	s_waitcnt lgkmcnt(3)
	v_mfma_f32_32x32x16_bf16 v[66:81], v[66:69], v[86:89], 0
	v_or_b32_e32 v0, s16, v146
	v_mfma_f32_32x32x16_bf16 v[82:97], v[82:85], v[86:89], 0
	s_waitcnt lgkmcnt(2)
	v_mfma_f32_32x32x16_bf16 v[82:97], v[126:129], v[138:141], v[82:97]
	v_sub_u32_e32 v126, v0, v162
	v_sub_u32_e32 v0, v162, v0
	v_cmp_lt_i32_e32 vcc, -1, v0
	v_cvt_f32_i32_e32 v126, v126
	v_mfma_f32_32x32x16_bf16 v[66:81], v[114:117], v[138:141], v[66:81]
	s_waitcnt lgkmcnt(1)
	v_mfma_f32_32x32x16_bf16 v[82:97], v[130:133], v[142:145], v[82:97]
	v_mfma_f32_32x32x16_bf16 v[66:81], v[118:121], v[142:145], v[66:81]
	s_waitcnt lgkmcnt(0)
	v_mfma_f32_32x32x16_bf16 v[82:97], v[134:137], v[194:197], v[82:97]
	v_mfma_f32_32x32x16_bf16 v[66:81], v[122:125], v[194:197], v[66:81]
	s_nop 10
	v_fmamk_f32 v82, v82, 0x3e38aa3b, v192
	v_fmamk_f32 v83, v83, 0x3e38aa3b, v160
	v_fmamk_f32 v84, v84, 0x3e38aa3b, v188
	v_fmamk_f32 v85, v85, 0x3e38aa3b, v189
	v_fmamk_f32 v86, v86, 0x3e38aa3b, v186
	v_fmamk_f32 v87, v87, 0x3e38aa3b, v187
	v_fmamk_f32 v88, v88, 0x3e38aa3b, v184
	v_fmac_f32_e32 v192, 0x3e38aa3b, v66
	v_cndmask_b32_e32 v115, v248, v192, vcc
	v_cmp_lt_i32_e32 vcc, 31, v0
	v_fmamk_f32 v66, v67, 0x3e38aa3b, v160
	v_fmamk_f32 v67, v68, 0x3e38aa3b, v188
	v_cndmask_b32_e32 v116, v248, v82, vcc
	v_cmp_lt_i32_e32 vcc, 0, v0
	v_fmac_f32_e32 v189, 0x3e38aa3b, v69
	v_fmamk_f32 v68, v70, 0x3e38aa3b, v186
	v_cndmask_b32_e32 v117, v248, v66, vcc
	v_cmp_lt_i32_e32 vcc, 32, v0
	v_fmac_f32_e32 v187, 0x3e38aa3b, v71
	v_fmamk_f32 v69, v72, 0x3e38aa3b, v184
	v_cndmask_b32_e32 v118, v248, v83, vcc
	v_cmp_lt_i32_e32 vcc, 1, v0
	v_fmamk_f32 v89, v89, 0x3e38aa3b, v185
	v_fmac_f32_e32 v185, 0x3e38aa3b, v73
	v_cndmask_b32_e32 v119, v248, v67, vcc
	v_cmp_lt_i32_e32 vcc, 33, v0
	v_fmamk_f32 v70, v74, 0x3e38aa3b, v182
	v_fmamk_f32 v90, v90, 0x3e38aa3b, v182
	v_cndmask_b32_e32 v120, v248, v84, vcc
	v_cmp_lt_i32_e32 vcc, 2, v0
	v_fmamk_f32 v91, v91, 0x3e38aa3b, v183
	v_fmac_f32_e32 v183, 0x3e38aa3b, v75
	v_cndmask_b32_e32 v121, v248, v189, vcc
	v_cmp_lt_i32_e32 vcc, 34, v0
	v_fmamk_f32 v71, v76, 0x3e38aa3b, v180
	v_fmamk_f32 v92, v92, 0x3e38aa3b, v180
	v_cndmask_b32_e32 v122, v248, v85, vcc
	v_cmp_lt_i32_e32 vcc, 3, v0
	v_fmamk_f32 v93, v93, 0x3e38aa3b, v181
	v_fmac_f32_e32 v181, 0x3e38aa3b, v77
	v_cndmask_b32_e32 v123, v248, v68, vcc
	v_cmp_lt_i32_e32 vcc, 35, v0
	v_fmamk_f32 v72, v78, 0x3e38aa3b, v178
	v_fmamk_f32 v94, v94, 0x3e38aa3b, v178
	v_cndmask_b32_e32 v124, v248, v86, vcc
	v_cmp_lt_i32_e32 vcc, 4, v0
	v_fmamk_f32 v95, v95, 0x3e38aa3b, v179
	v_fmamk_f32 v96, v96, 0x3e38aa3b, v176
	v_cndmask_b32_e32 v125, v248, v187, vcc
	v_cmp_lt_i32_e32 vcc, 36, v0
	v_fmac_f32_e32 v179, 0x3e38aa3b, v79
	v_fmamk_f32 v73, v80, 0x3e38aa3b, v176
	v_cndmask_b32_e32 v127, v248, v87, vcc
	v_cmp_lt_i32_e32 vcc, 5, v0
	v_fmamk_f32 v97, v97, 0x3e38aa3b, v177
	v_fmac_f32_e32 v177, 0x3e38aa3b, v81
	v_cndmask_b32_e32 v128, v248, v69, vcc
	v_cmp_lt_i32_e32 vcc, 37, v0
	v_max3_f32 v66, v116, s54, v118
	v_max3_f32 v66, v66, v120, v122
	v_cndmask_b32_e32 v129, v248, v88, vcc
	v_cmp_lt_i32_e32 vcc, 6, v0
	v_max3_f32 v66, v66, v124, v127
	s_nop 0
	v_cndmask_b32_e32 v130, v248, v185, vcc
	v_cmp_lt_i32_e32 vcc, 38, v0
	s_nop 1
	v_cndmask_b32_e32 v131, v248, v89, vcc
	v_cmp_lt_i32_e32 vcc, 15, v0
	v_max3_f32 v66, v66, v129, v131
	s_nop 0
	v_cndmask_b32_e32 v137, v248, v70, vcc
	v_cmp_lt_i32_e32 vcc, 47, v0
	s_nop 1
	v_cndmask_b32_e32 v141, v248, v90, vcc
	v_cmp_lt_i32_e32 vcc, 16, v0
	s_nop 1
	v_cndmask_b32_e32 v145, v248, v183, vcc
	v_cmp_lt_i32_e32 vcc, 48, v0
	s_nop 1
	v_cndmask_b32_e32 v164, v248, v91, vcc
	v_cmp_lt_i32_e32 vcc, 17, v0
	v_max3_f32 v66, v66, v141, v164
	s_nop 0
	v_cndmask_b32_e32 v162, v248, v71, vcc
	v_cmp_lt_i32_e32 vcc, 49, v0
	s_nop 1
	v_cndmask_b32_e32 v165, v248, v92, vcc
	v_cmp_lt_i32_e32 vcc, 18, v0
	s_nop 1
	v_cndmask_b32_e32 v168, v248, v181, vcc
	v_cmp_lt_i32_e32 vcc, 50, v0
	s_nop 1
	v_cndmask_b32_e32 v170, v248, v93, vcc
	v_cmp_lt_i32_e32 vcc, 19, v0
	v_max3_f32 v66, v66, v165, v170
	s_nop 0
	v_cndmask_b32_e32 v171, v248, v72, vcc
	v_cmp_lt_i32_e32 vcc, 51, v0
	s_nop 1
	v_cndmask_b32_e32 v176, v248, v94, vcc
	v_cmp_lt_i32_e32 vcc, 20, v0
	s_nop 1
	v_cndmask_b32_e32 v178, v248, v179, vcc
	v_cmp_lt_i32_e32 vcc, 52, v0
	s_nop 1
	v_cndmask_b32_e32 v179, v248, v95, vcc
	v_cmp_lt_i32_e32 vcc, 21, v0
	v_max3_f32 v66, v66, v176, v179
	s_nop 0
	v_cndmask_b32_e32 v180, v248, v73, vcc
	v_cmp_lt_i32_e32 vcc, 53, v0
	s_nop 1
	v_cndmask_b32_e32 v181, v248, v96, vcc
	v_cmp_lt_i32_e32 vcc, 22, v0
	s_nop 1
	v_cndmask_b32_e32 v182, v248, v177, vcc
	v_cmp_lt_i32_e32 vcc, 54, v0
	v_max_f32_e32 v0, 0xff800000, v115
	v_max3_f32 v0, v0, v117, v119
	v_max3_f32 v0, v0, v121, v123
	v_max3_f32 v0, v0, v125, v128
	v_max3_f32 v0, v0, v130, v137
	v_cndmask_b32_e32 v183, v248, v97, vcc
	v_max3_f32 v0, v0, v145, v162
	v_max3_f32 v0, v0, v168, v171
	v_max3_f32 v66, v66, v181, v183
	v_max3_f32 v0, v0, v178, v180
	v_add_f32_e32 v66, v157, v66
	v_max3_f32 v0, v0, v182, v66
	v_fmac_f32_e32 v0, v160, v126
	v_mov_b32_e32 v66, v0
	s_nop 1
	v_permlane32_swap_b32_e32 v0, v66
	ds_read_b128 v[94:97], v212 offset:53248
	ds_read_b128 v[90:93], v212 offset:53280
	ds_read_b128 v[86:89], v212 offset:57856
	ds_read_b128 v[82:85], v212 offset:57888
	s_waitcnt lgkmcnt(4)
; DI float fexp2(float x) { return __builtin_amdgcn_exp2f(x); }
; DI void diff_attn_phase(int wv, LAS unsigned char* lds, const bf16_t* qk, const bf16_t* vt, bf16_t* ob, const float* lq1, const float* lk1, const float* lq2, const float* lk2,
;                         const float* subg, int layer_idx) {
;     ...
;                 {
;                     const float mn = fmaxf(m, mx), alpha = fexp2(m - mn); m = mn; l *= alpha;
; #pragma unroll
;                     for (int d = 0; d < 4; ++d) O[d] = O[d] * alpha;
;                 }
;                 const float off = base - m, off1 = off + b32;
;                 float ps = 0.f;
; #pragma unroll
;                 for (int i = 0; i < 16; ++i) { S0[i] = fexp2(S0[i] + off); S1[i] = fexp2(S1[i] + off1); ps += S0[i] + S1[i]; }
;                 l += ps;
;                 const bf16x8 p0 = pack8(S0, 0), p1 = pack8(S0, 1), p2 = pack8(S1, 0), p3 = pack8(S1, 1);
	v_max3_f32 v0, v218, v0, v66
	v_sub_f32_e32 v66, v218, v0
	v_exp_f32_e32 v114, v66
	v_fma_f32 v126, v160, v126, -v0
	v_add_f32_e32 v157, v157, v126
	v_add_f32_e32 v0, v115, v126
	v_pk_mul_f32 v[64:65], v[64:65], v[114:115] op_sel_hi:[1,0]
	v_pk_mul_f32 v[62:63], v[62:63], v[114:115] op_sel_hi:[1,0]
	v_pk_mul_f32 v[60:61], v[60:61], v[114:115] op_sel_hi:[1,0]
	v_pk_mul_f32 v[58:59], v[58:59], v[114:115] op_sel_hi:[1,0]
	v_pk_mul_f32 v[56:57], v[56:57], v[114:115] op_sel_hi:[1,0]
	v_pk_mul_f32 v[54:55], v[54:55], v[114:115] op_sel_hi:[1,0]
	v_pk_mul_f32 v[52:53], v[52:53], v[114:115] op_sel_hi:[1,0]
	v_pk_mul_f32 v[50:51], v[50:51], v[114:115] op_sel_hi:[1,0]
	v_pk_mul_f32 v[48:49], v[48:49], v[114:115] op_sel_hi:[1,0]
	v_pk_mul_f32 v[46:47], v[46:47], v[114:115] op_sel_hi:[1,0]
	v_pk_mul_f32 v[44:45], v[44:45], v[114:115] op_sel_hi:[1,0]
	v_pk_mul_f32 v[42:43], v[42:43], v[114:115] op_sel_hi:[1,0]
	v_pk_mul_f32 v[40:41], v[40:41], v[114:115] op_sel_hi:[1,0]
	v_pk_mul_f32 v[38:39], v[38:39], v[114:115] op_sel_hi:[1,0]
	v_pk_mul_f32 v[36:37], v[36:37], v[114:115] op_sel_hi:[1,0]
	v_pk_mul_f32 v[34:35], v[34:35], v[114:115] op_sel_hi:[1,0]
	v_pk_mul_f32 v[32:33], v[32:33], v[114:115] op_sel_hi:[1,0]
	v_pk_mul_f32 v[30:31], v[30:31], v[114:115] op_sel_hi:[1,0]
	v_pk_mul_f32 v[28:29], v[28:29], v[114:115] op_sel_hi:[1,0]
	v_pk_mul_f32 v[26:27], v[26:27], v[114:115] op_sel_hi:[1,0]
	v_pk_mul_f32 v[24:25], v[24:25], v[114:115] op_sel_hi:[1,0]
	v_pk_mul_f32 v[22:23], v[22:23], v[114:115] op_sel_hi:[1,0]
	v_pk_mul_f32 v[20:21], v[20:21], v[114:115] op_sel_hi:[1,0]
	v_pk_mul_f32 v[18:19], v[18:19], v[114:115] op_sel_hi:[1,0]
	v_pk_mul_f32 v[16:17], v[16:17], v[114:115] op_sel_hi:[1,0]
	v_pk_mul_f32 v[14:15], v[14:15], v[114:115] op_sel_hi:[1,0]
	v_pk_mul_f32 v[12:13], v[12:13], v[114:115] op_sel_hi:[1,0]
	v_pk_mul_f32 v[10:11], v[10:11], v[114:115] op_sel_hi:[1,0]
	v_pk_mul_f32 v[8:9], v[8:9], v[114:115] op_sel_hi:[1,0]
	v_exp_f32_e32 v115, v0
	v_add_f32_e32 v0, v116, v157
	v_add_f32_e32 v116, v119, v126
	v_exp_f32_e32 v160, v0
	v_add_f32_e32 v0, v117, v126
	v_exp_f32_e32 v117, v116
	v_add_f32_e32 v116, v120, v157
	v_exp_f32_e32 v184, v116
	v_add_f32_e32 v116, v121, v126
	v_exp_f32_e32 v134, v116
	v_add_f32_e32 v116, v122, v157
	v_exp_f32_e32 v136, v116
	v_add_f32_e32 v116, v125, v126
	v_exp_f32_e32 v138, v116
	v_add_f32_e32 v116, v127, v157
	v_exp_f32_e32 v140, v116
	v_add_f32_e32 v116, v130, v126
	v_exp_f32_e32 v142, v116
	v_add_f32_e32 v116, v131, v157
	v_add_f32_e32 v121, v141, v157
	v_exp_f32_e32 v144, v116
	v_add_f32_e32 v116, v145, v126
	v_add_f32_e32 v120, v129, v157
	v_exp_f32_e32 v129, v121
	v_add_f32_e32 v121, v162, v126
	v_exp_f32_e32 v162, v116
	v_add_f32_e32 v116, v164, v157
	v_exp_f32_e32 v164, v116
	v_add_f32_e32 v116, v168, v126
	v_exp_f32_e32 v168, v116
	v_add_f32_e32 v116, v170, v157
	v_exp_f32_e32 v170, v116
	v_add_f32_e32 v116, v178, v126
	ds_read_b128 v[78:81], v212 offset:62464
	ds_read_b128 v[74:77], v212 offset:62496
	ds_read_b128 v[70:73], v213 offset:13824
	ds_read_b128 v[66:69], v213 offset:13856
	v_exp_f32_e32 v132, v0
	v_add_f32_e32 v0, v118, v157
	v_add_f32_e32 v118, v123, v126
	v_add_f32_e32 v123, v176, v157
	v_exp_f32_e32 v176, v116
	v_add_f32_e32 v116, v179, v157
	v_add_f32_e32 v119, v124, v157
	v_add_f32_e32 v122, v165, v157
	v_exp_f32_e32 v178, v116
	v_add_f32_e32 v116, v182, v126
	v_exp_f32_e32 v185, v119
	v_add_f32_e32 v119, v128, v126
	v_exp_f32_e32 v128, v120
	v_add_f32_e32 v120, v137, v126
	v_exp_f32_e32 v130, v122
	v_add_f32_e32 v122, v171, v126
	v_exp_f32_e32 v131, v123
	v_add_f32_e32 v123, v180, v126
	v_add_f32_e32 v124, v181, v157
	v_exp_f32_e32 v180, v116
	v_add_f32_e32 v116, v183, v157
	v_exp_f32_e32 v0, v0
	v_exp_f32_e32 v118, v118
	v_exp_f32_e32 v119, v119
	v_exp_f32_e32 v120, v120
	v_exp_f32_e32 v121, v121
	v_exp_f32_e32 v122, v122
	v_exp_f32_e32 v123, v123
	v_exp_f32_e32 v137, v124
	v_exp_f32_e32 v182, v116
	v_pk_mul_f32 v[6:7], v[6:7], v[114:115] op_sel_hi:[1,0]
	v_pk_mul_f32 v[4:5], v[4:5], v[114:115] op_sel_hi:[1,0]
	v_pk_mul_f32 v[2:3], v[2:3], v[114:115] op_sel_hi:[1,0]
	v_add_f32_e32 v133, v115, v160
	v_add_f32_e32 v135, v117, v184
	v_add_f32_e32 v139, v118, v185
	v_add_f32_e32 v143, v119, v128
	v_add_f32_e32 v163, v120, v129
	v_add_f32_e32 v169, v121, v130
	v_add_f32_e32 v177, v122, v131
	v_add_f32_e32 v181, v123, v137
	v_cvt_pk_bf16_f32 v116, v115, v132
	v_cvt_pk_bf16_f32 v117, v117, v134
	v_cvt_pk_bf16_f32 v118, v118, v138
	v_cvt_pk_bf16_f32 v119, v119, v142
	v_cvt_pk_bf16_f32 v120, v120, v162
	v_cvt_pk_bf16_f32 v121, v121, v168
	v_cvt_pk_bf16_f32 v122, v122, v176
	v_cvt_pk_bf16_f32 v123, v123, v180
	v_cvt_pk_bf16_f32 v124, v160, v0
	v_cvt_pk_bf16_f32 v125, v184, v136
	v_cvt_pk_bf16_f32 v126, v185, v140
	v_cvt_pk_bf16_f32 v127, v128, v144
	v_cvt_pk_bf16_f32 v128, v129, v164
	v_cvt_pk_bf16_f32 v129, v130, v170
	v_cvt_pk_bf16_f32 v130, v131, v178
	v_cvt_pk_bf16_f32 v131, v137, v182
	s_waitcnt lgkmcnt(5)
; #define LAS __attribute__((address_space(3)))
; #define MFMA32(a, b, c) __builtin_amdgcn_mfma_f32_32x32x16_bf16((a), (b), (c), 0, 0, 0)
; DI void diff_attn_phase(int wv, LAS unsigned char* lds, const bf16_t* qk, const bf16_t* vt, bf16_t* ob, const float* lq1, const float* lk1, const float* lq2, const float* lk2,
;                         const float* subg, int layer_idx) {
;     ...
;                 l += ps;
;                 const bf16x8 p0 = pack8(S0, 0), p1 = pack8(S0, 1), p2 = pack8(S1, 0), p3 = pack8(S1, 1);
;                 __builtin_amdgcn_sched_barrier(0);
; #pragma unroll
;                 for (int d = 0; d < 4; ++d) { O[d] = MFMA32(vf[d][0], p0, O[d]); O[d] = MFMA32(vf[d][1], p1, O[d]); }
;                 __builtin_amdgcn_sched_barrier(0);
; #pragma unroll
;                 for (int d = 0; d < 4; ++d)
; #pragma unroll
;                     for (int s2 = 0; s2 < 2; ++s2) vf[d][s2] = *(const LAS bf16x8*)(buf + voff + d * 32 * DA_VP + (32 + 16 * s2) * 2);
; #pragma unroll
;                 for (int d = 0; d < 4; ++d) { O[d] = MFMA32(vf[d][0], p2, O[d]); O[d] = MFMA32(vf[d][1], p3, O[d]); }
	v_mfma_f32_32x32x16_bf16 v[34:49], v[86:89], v[116:119], v[34:49]
	s_waitcnt lgkmcnt(4)
	v_mfma_f32_32x32x16_bf16 v[34:49], v[82:85], v[120:123], v[34:49]
	v_add_f32_e64 v82, v132, v0
	v_add_f32_e64 v83, v133, v1
	s_waitcnt lgkmcnt(3)
	v_mfma_f32_32x32x16_bf16 v[18:33], v[78:81], v[116:119], v[18:33]
	v_add_f32_e64 v78, v82, v82
	v_add_f32_e64 v79, v82, v83
	v_mov_b32_e32 v137, v79
	v_add_f32_e64 v78, v134, v136
	v_add_f32_e64 v79, v135, v137
	v_pk_add_f32 v[78:79], v[78:79], v[78:79] op_sel_hi:[0,1]
	v_mov_b32_e32 v141, v79
	v_pk_add_f32 v[78:79], v[138:139], v[140:141]
	v_mfma_f32_32x32x16_bf16 v[50:65], v[94:97], v[116:119], v[50:65]
	v_pk_add_f32 v[78:79], v[78:79], v[78:79] op_sel_hi:[0,1]
	v_mov_b32_e32 v145, v79
	s_waitcnt lgkmcnt(1)
	v_mfma_f32_32x32x16_bf16 v[2:17], v[70:73], v[116:119], v[2:17]
	v_mfma_f32_32x32x16_bf16 v[18:33], v[74:77], v[120:123], v[18:33]
	v_add_f32_e64 v74, v142, v144
	v_add_f32_e64 v75, v143, v145
	v_pk_add_f32 v[74:75], v[74:75], v[74:75] op_sel_hi:[0,1]
	v_mov_b32_e32 v165, v75
	v_pk_add_f32 v[74:75], v[162:163], v[164:165]
	s_nop 0
	v_pk_add_f32 v[74:75], v[74:75], v[74:75] op_sel_hi:[0,1]
	v_mfma_f32_32x32x16_bf16 v[50:65], v[90:93], v[120:123], v[50:65]
	v_mov_b32_e32 v171, v75
	v_add_f32_e64 v70, v168, v170
	v_add_f32_e64 v71, v169, v171
	v_pk_add_f32 v[70:71], v[70:71], v[70:71] op_sel_hi:[0,1]
	v_mov_b32_e32 v179, v71
	v_pk_add_f32 v[70:71], v[176:177], v[178:179]
	s_waitcnt lgkmcnt(0)
	v_mfma_f32_32x32x16_bf16 v[2:17], v[66:69], v[120:123], v[2:17]
	v_pk_add_f32 v[70:71], v[70:71], v[70:71] op_sel_hi:[0,1]
	v_mov_b32_e32 v183, v71
	v_pk_add_f32 v[70:71], v[180:181], v[182:183]
	s_nop 0
	v_add_f32_e32 v0, v70, v71
	ds_read_b128 v[66:69], v212 offset:53312
	v_fmac_f32_e32 v0, v159, v114
	v_mov_b32_e32 v159, v0
	s_waitcnt lgkmcnt(0)
	v_mfma_f32_32x32x16_bf16 v[50:65], v[66:69], v[124:127], v[50:65]
	ds_read_b128 v[66:69], v212 offset:53344
	s_waitcnt lgkmcnt(0)
	v_mfma_f32_32x32x16_bf16 v[50:65], v[66:69], v[128:131], v[50:65]
	ds_read_b128 v[66:69], v212 offset:57920
	s_waitcnt lgkmcnt(0)
	v_mfma_f32_32x32x16_bf16 v[34:49], v[66:69], v[124:127], v[34:49]
	ds_read_b128 v[66:69], v212 offset:57952
	s_waitcnt lgkmcnt(0)
	v_mfma_f32_32x32x16_bf16 v[34:49], v[66:69], v[128:131], v[34:49]
	ds_read_b128 v[66:69], v212 offset:62528
	s_waitcnt lgkmcnt(0)
	v_mfma_f32_32x32x16_bf16 v[18:33], v[66:69], v[124:127], v[18:33]
	ds_read_b128 v[66:69], v212 offset:62560
	s_waitcnt lgkmcnt(0)
	v_mfma_f32_32x32x16_bf16 v[18:33], v[66:69], v[128:131], v[18:33]
	ds_read_b128 v[66:69], v213 offset:13888
	s_waitcnt lgkmcnt(0)
	v_mfma_f32_32x32x16_bf16 v[2:17], v[66:69], v[124:127], v[2:17]
	ds_read_b128 v[66:69], v213 offset:13920
	s_waitcnt lgkmcnt(0)
	v_mfma_f32_32x32x16_bf16 v[2:17], v[66:69], v[128:131], v[2:17]
